# EpiFfnUp pre_issue: wave-disjoint WAW wait in front of the second predicated load removed
# speedup vs baseline: 1.0386x; 1.0010x over previous
;     __device__ __forceinline__ void pre_issue(const pg8::Unit& u, int tid, f32x4& v) const {
;         if (tid < 256) v = *(const f32x4*)(ss + ((size_t)u.pm * 256 + tid) * 4);
;         else v[0] = cf[(size_t)(u.pm < 64 ? (u.pm >> 3) : 8) * DFF + u.pn * 256 + (tid - 256)]; }
;     __device__ __forceinline__ void pre_commit(int tid, int par, const f32x4& v) const {
.LBB0_1709:
	s_andn2_saveexec_b64 s[50:51], s[50:51]
	s_cbranch_execz .LBB0_1711
	s_ashr_i32 s43, s42, 31
	s_lshl_b64 s[52:53], s[42:43], 12
	v_lshl_add_u64 v[2:3], v[144:145], 0, s[52:53]
	global_load_dwordx4 v[2:5], v[2:3], off

;     __device__ __forceinline__ void pre_issue(const pg8::Unit& u, int tid, f32x4& v) const {
;         if (tid < 256) v = *(const f32x4*)(ss + ((size_t)u.pm * 256 + tid) * 4);
;         else v[0] = cf[(size_t)(u.pm < 64 ? (u.pm >> 3) : 8) * DFF + u.pn * 256 + (tid - 256)]; }
;     __device__ __forceinline__ void pre_commit(int tid, int par, const f32x4& v) const {
.LBB0_3335:
	s_andn2_saveexec_b64 s[10:11], s[10:11]
	s_cbranch_execz .LBB0_3337
	s_ashr_i32 s29, s28, 31
	s_lshl_b64 s[36:37], s[28:29], 12
	v_lshl_add_u64 v[2:3], v[144:145], 0, s[36:37]
	global_load_dwordx4 v[2:5], v[2:3], off
